# P4 output pass split 6/10 by workgroup group; P3 LRU chunk-carry items moved from workgroups 128..131 (which also run an S5 GEMM unit) to workgroups 0..3
# speedup vs baseline: 1.0066x; 1.0040x over previous
; __device__ __forceinline__ void phase_carries(float* GLAS, const float* GDEC, const float* LRUP, float* LRUE, int gid, int gsz) {
;     for (int e = gid; e < 65536 + 2048; e += gsz) {
;         if (e < 65536) { const int bh = e >> 11, dv = e & 2047, d = dv >> 6; float S = 0.f;
.LBB0_532:
	v_mov_b32_e32 v0, v216
	s_mov_b64 s[6:7], s[0:1]
	s_mov_b32 s2, s56
	s_mov_b32 s3, s55
	s_nop 0
	v_lshl_add_u32 v72, s3, 9, v0
	s_mov_b32 s3, 0x10000
	v_cmp_gt_i32_e32 vcc, s3, v72
	s_and_saveexec_b64 s[4:5], vcc
	s_cbranch_execz .LBB0_541
	s_load_dwordx2 s[14:15], s[6:7], 0x118
	s_mov_b32 s2, 0x10000
	v_and_b32_e32 v4, 0xff, v0
	v_lshlrev_b32_e32 v0, 2, v4
	s_mov_b64 s[6:7], 0
	s_waitcnt lgkmcnt(0)
	s_add_u32 s8, s14, 0xc800000
	s_addc_u32 s9, s15, 0
	s_add_u32 s10, s14, 0x400000
	s_addc_u32 s11, s15, 0
	s_add_u32 s12, s14, 0x300000
	s_addc_u32 s13, s15, 0
	s_add_u32 s14, s14, 0x380000
	s_addc_u32 s15, s15, 0
	v_lshl_add_u64 v[2:3], s[14:15], 0, v[0:1]
	v_lshlrev_b32_e32 v73, 2, v4
	s_branch .LBB0_535
